# phase_a weight transposes: next tile fetched during the current tile (register double buffer)
# speedup vs baseline: 1.0056x; 1.0008x over previous
.LBB0_21:
	v_mov_b32_e32 v133, 0
	global_load_dword v202, v133, s[44:45] offset:256 sc1
	global_load_dword v201, v133, s[44:45] offset:512 sc1
	global_load_dword v200, v133, s[44:45] offset:768 sc1
	global_load_dword v199, v133, s[44:45] offset:1024 sc1
	global_load_dword v196, v133, s[44:45] offset:1280 sc1
	global_load_dword v192, v133, s[44:45] offset:1536 sc1
	global_load_dword v191, v133, s[44:45] offset:1792 sc1
	global_load_dword v190, v133, s[44:45] offset:2048 sc1
	global_load_dword v189, v133, s[44:45] offset:2304 sc1
	global_load_dword v187, v133, s[44:45] offset:2560 sc1
	global_load_dword v186, v133, s[44:45] offset:2816 sc1
	global_load_dword v185, v133, s[44:45] offset:3072 sc1
	global_load_dword v184, v133, s[44:45] offset:3328 sc1
	global_load_dword v137, v133, s[44:45] offset:3584 sc1
	global_load_dword v135, v133, s[44:45] offset:3840 sc1
	v_mov_b32_e32 v0, 0x1000
	global_load_dword v131, v0, s[44:45] sc1
	v_writelane_b32 v254, s36, 57
	s_cmpk_gt_i32 s2, 0x8ff
	v_lshrrev_b32_e32 v193, 4, v188
	v_writelane_b32 v255, s43, 0
	v_writelane_b32 v255, s44, 1
	v_writelane_b32 v255, s45, 2
	v_writelane_b32 v254, s37, 58
	v_writelane_b32 v255, s46, 3
	v_writelane_b32 v254, s38, 59
	v_writelane_b32 v255, s47, 4
	v_writelane_b32 v254, s39, 60
	v_writelane_b32 v255, s48, 5
	v_writelane_b32 v254, s40, 61
	v_writelane_b32 v255, s49, 6
	v_writelane_b32 v254, s41, 62
	v_writelane_b32 v255, s50, 7
	v_lshlrev_b32_e32 v130, 2, v188
	v_lshrrev_b32_e32 v194, 3, v188
	v_lshrrev_b32_e32 v197, 5, v188
	v_and_b32_e32 v198, 31, v188
	v_lshlrev_b32_e32 v128, 4, v188
	v_writelane_b32 v254, s42, 63
	v_writelane_b32 v255, s51, 8
	s_cbranch_scc1 .LBB0_52
	v_lshlrev_b32_e32 v0, 3, v188
	v_and_b32_e32 v134, 60, v130
	v_and_b32_e32 v136, 56, v0
	v_readlane_b32 s8, v254, 41
	v_lshlrev_b32_e32 v132, 2, v134
	v_mul_u32_u24_e32 v1, 0x41, v136
	v_readlane_b32 s9, v254, 42
	v_readlane_b32 s10, v254, 43
	v_readlane_b32 s11, v254, 44
	v_readlane_b32 s12, v254, 45
	v_readlane_b32 s13, v254, 46
	v_readlane_b32 s14, v254, 47
	v_readlane_b32 s15, v254, 48
	v_readlane_b32 s16, v254, 49
	v_readlane_b32 s17, v254, 50
	v_readlane_b32 s18, v254, 51
	v_readlane_b32 s19, v254, 52
	v_readlane_b32 s20, v254, 53
	v_readlane_b32 s21, v254, 54
	v_readlane_b32 s22, v254, 55
	v_readlane_b32 s23, v254, 56
	v_lshlrev_b32_e32 v0, 2, v194
	v_lshlrev_b32_e32 v1, 2, v1
	v_lshl_add_u64 v[138:139], s[8:9], 0, v[132:133]
	v_readlane_b32 s8, v254, 25
	v_add3_u32 v206, 0, v0, v1
	v_add3_u32 v207, 0, v1, v0
	v_lshlrev_b32_e32 v0, 11, v197
	s_add_i32 s0, 0, 0x10000
	v_lshlrev_b32_e32 v2, 2, v198
	v_readlane_b32 s12, v254, 29
	v_readlane_b32 s13, v254, 30
	v_readlane_b32 s14, v254, 31
	v_readlane_b32 s15, v254, 32
	v_readlane_b32 s16, v254, 33
	v_readlane_b32 s17, v254, 34
	v_readlane_b32 s18, v254, 35
	v_readlane_b32 s19, v254, 36
	v_readlane_b32 s20, v254, 37
	v_readlane_b32 s21, v254, 38
	v_readlane_b32 s22, v254, 39
	v_readlane_b32 s23, v254, 40
	v_add3_u32 v208, s0, v0, v2
	v_and_b32_e32 v0, 0x3e0, v188
	v_readlane_b32 s12, v254, 9
	v_lshlrev_b32_e32 v0, 2, v0
	v_readlane_b32 s14, v254, 11
	v_readlane_b32 s15, v254, 12
	v_mov_b32_e32 v129, v133
	v_add3_u32 v209, s0, v0, v2
	v_lshl_add_u64 v[146:147], s[14:15], 0, v[128:129]
	s_mov_b64 s[0:1], 0x2000
	v_readlane_b32 s9, v254, 26
	v_readlane_b32 s24, v254, 21
	v_readlane_b32 s25, v254, 22
	v_readlane_b32 s26, v254, 23
	v_readlane_b32 s27, v254, 24
	v_lshl_add_u64 v[148:149], v[146:147], 0, s[0:1]
	s_mov_b64 s[0:1], 0x6000
	v_add_u32_e32 v203, 0, v132
	v_lshl_add_u64 v[140:141], s[8:9], 0, v[132:133]
	v_lshl_add_u64 v[142:143], s[26:27], 0, v[132:133]
	v_lshl_add_u64 v[144:145], s[24:25], 0, v[132:133]
	v_or_b32_e32 v132, 0x4000, v128
	v_lshl_add_u64 v[152:153], v[146:147], 0, s[0:1]
	s_mov_b64 s[0:1], 0xa000
	v_lshl_add_u64 v[150:151], s[14:15], 0, v[132:133]
	v_or_b32_e32 v132, 0x8000, v128
	v_lshl_add_u64 v[156:157], v[146:147], 0, s[0:1]
	v_or_b32_e32 v0, 0xc00, v188
	s_movk_i32 s0, 0xe00
	v_lshl_add_u64 v[154:155], s[14:15], 0, v[132:133]
	v_lshlrev_b32_e32 v132, 4, v0
	v_cmp_gt_u32_e64 s[0:1], s0, v0
	v_mul_u32_u24_e32 v0, 0xc0000, v197
	v_readlane_b32 s10, v254, 27
	v_readlane_b32 s11, v254, 28
	v_readlane_b32 s13, v254, 10
	v_readlane_b32 s16, v254, 13
	v_readlane_b32 s17, v254, 14
	v_readlane_b32 s18, v254, 15
	v_readlane_b32 s20, v254, 17
	v_readlane_b32 s21, v254, 18
	v_add_u32_e32 v129, 0, v128
	s_mov_b64 s[6:7], 0xe000
	v_mul_hi_u32_u24_e32 v1, 0xc0000, v197
	v_or_b32_e32 v0, v0, v2
	s_mov_b32 s5, 0
	v_mul_u32_u24_e32 v204, 0x104, v193
	v_add_u32_e32 v205, 32, v193
	v_add_u32_e32 v210, 0x2000, v129
	v_add_u32_e32 v211, 0x4000, v129
	s_movk_i32 s10, 0x6000
	v_add_u32_e32 v212, 0x6000, v129
	v_add_u32_e32 v213, 0x8000, v129
	v_add_u32_e32 v214, 0xa000, v129
	s_movk_i32 s11, 0xc00
	v_lshl_add_u64 v[158:159], s[14:15], 0, v[132:133]
	s_mov_b32 s12, 0xc000
	v_add_u32_e32 v215, 0xc000, v129
	v_lshl_add_u64 v[160:161], v[146:147], 0, s[6:7]
	v_add_u32_e32 v216, 0xe000, v129
	v_lshl_add_u64 v[162:163], s[20:21], 0, v[0:1]
	v_lshl_add_u32 v217, v197, 8, 0
	s_movk_i32 s13, 0x3000
	s_mov_b32 s14, 0x9000
	s_mov_b32 s15, 0xf000
	s_mov_b32 s16, 0x12000
	s_mov_b32 s17, 0x15000
	s_mov_b32 s18, s2
	v_readlane_b32 s19, v254, 16
	v_readlane_b32 s22, v254, 19
	v_readlane_b32 s23, v254, 20
	s_mov_b32 s22, 0
	s_branch .LBB0_24
.LBB0_23:
	s_mov_b32 s22, 0
	s_cmp_eq_u32 s23, 0
	s_cbranch_scc1 .Lpa_tail_done
	s_waitcnt vmcnt(1)
	v_mov_b32_e32 v100, v108
	v_mov_b32_e32 v101, v109
	v_mov_b32_e32 v102, v110
	v_mov_b32_e32 v103, v111
	v_mov_b32_e32 v104, v112
	v_mov_b32_e32 v105, v113
	v_mov_b32_e32 v106, v114
	v_mov_b32_e32 v107, v115
	s_mov_b32 s22, 1

.LBB0_24:
	s_mov_b32 s23, 0
	s_cmpk_lt_i32 s18, 0xc0
	s_cbranch_scc1 .Lpa_pf_done
	s_add_i32 s25, s18, s3
	s_cmpk_gt_i32 s25, 0x8bf
	s_cbranch_scc1 .Lpa_pf_done
	s_cmpk_gt_i32 s25, 0x7bf
	s_cbranch_scc1 .Lpa_pf_out1
	s_cmpk_gt_i32 s25, 0x5bf
	s_cbranch_scc1 .Lpa_pf_in1
	s_cmpk_gt_i32 s25, 0x4bf
	s_cbranch_scc1 .Lpa_pf_out0
	s_add_i32 s26, s25, 0xffffff40
	s_and_b32 s34, s26, 0xffffffc0
	s_lshl_b32 s26, s26, 6
	s_and_b32 s27, s26, 0xfc0
	s_lshl_b32 s52, s27, 2
	s_mov_b32 s53, 0
	v_mov_b32_e32 v119, 0
	v_or_b32_e32 v116, s34, v193
	v_lshl_add_u64 v[120:121], v[144:145], 0, s[52:53]
	v_lshlrev_b32_e32 v118, 12, v116
	v_lshl_add_u64 v[108:109], v[118:119], 2, v[120:121]
	global_load_dwordx4 v[108:111], v[108:109], off
	v_add_lshl_u32 v118, s34, v205, 12
	v_lshl_add_u64 v[112:113], v[118:119], 2, v[120:121]
	global_load_dwordx4 v[112:115], v[112:113], off
	s_branch .Lpa_pf_set
.Lpa_pf_out0:
	s_add_i32 s26, s25, 0xfffffb40
	s_lshr_b32 s27, s26, 4
	s_lshl_b32 s34, s27, 10
	s_lshl_b32 s26, s26, 6
	s_lshl_b32 s29, s27, 6
	s_sub_i32 s34, s26, s34
	s_ashr_i32 s35, s34, 31
	v_mov_b32_e32 v119, 0
	v_or_b32_e32 v116, s29, v193
	v_lshl_add_u64 v[120:121], s[34:35], 2, v[142:143]
	v_lshlrev_b32_e32 v118, 10, v116
	v_lshl_add_u64 v[108:109], v[118:119], 2, v[120:121]
	global_load_dwordx4 v[108:111], v[108:109], off
	v_add_lshl_u32 v118, s29, v205, 10
	v_lshl_add_u64 v[112:113], v[118:119], 2, v[120:121]
	global_load_dwordx4 v[112:115], v[112:113], off
	s_branch .Lpa_pf_set
.Lpa_pf_in1:
	s_add_i32 s26, s25, 0xfffffa40
	s_lshr_b32 s27, s26, 5
	s_lshl_b32 s34, s27, 11
	s_lshl_b32 s26, s26, 6
	s_lshl_b32 s29, s27, 6
	s_sub_i32 s34, s26, s34
	s_ashr_i32 s35, s34, 31
	v_mov_b32_e32 v119, 0
	v_or_b32_e32 v116, s29, v193
	v_lshl_add_u64 v[120:121], s[34:35], 2, v[140:141]
	v_lshlrev_b32_e32 v118, 11, v116
	v_lshl_add_u64 v[108:109], v[118:119], 2, v[120:121]
	global_load_dwordx4 v[108:111], v[108:109], off
	v_add_lshl_u32 v118, s29, v205, 11
	v_lshl_add_u64 v[112:113], v[118:119], 2, v[120:121]
	global_load_dwordx4 v[112:115], v[112:113], off
	s_branch .Lpa_pf_set
.Lpa_pf_out1:
	s_add_i32 s26, s25, 0xfffff840
	s_lshr_b32 s27, s26, 4
	s_lshl_b32 s34, s27, 10
	s_lshl_b32 s26, s26, 6
	s_lshl_b32 s29, s27, 6
	s_sub_i32 s34, s26, s34
	s_ashr_i32 s35, s34, 31
	v_mov_b32_e32 v119, 0
	v_or_b32_e32 v116, s29, v193
	v_lshl_add_u64 v[120:121], s[34:35], 2, v[138:139]
	v_lshlrev_b32_e32 v118, 10, v116
	v_lshl_add_u64 v[108:109], v[118:119], 2, v[120:121]
	global_load_dwordx4 v[108:111], v[108:109], off
	v_add_lshl_u32 v118, s29, v205, 10
	v_lshl_add_u64 v[112:113], v[118:119], 2, v[120:121]
	global_load_dwordx4 v[112:115], v[112:113], off
.Lpa_pf_set:
	s_mov_b32 s23, 1

.LBB0_35:
	s_andn2_b64 vcc, exec, s[6:7]
	s_cbranch_vccnz .LBB0_37
	s_add_i32 s4, s18, 0xfffff840
	s_lshr_b32 s8, s4, 4
	s_lshl_b32 s6, s8, 10
	s_lshl_b32 s4, s4, 6
	s_lshl_b32 s9, s8, 6
	s_sub_i32 s6, s4, s6
	s_ashr_i32 s7, s6, 31
	s_cmp_lg_u32 s22, 0
	s_cbranch_scc1 .Lpa_have_out1
	v_or_b32_e32 v0, s9, v193
	v_lshl_add_u64 v[4:5], s[6:7], 2, v[138:139]
	v_lshlrev_b32_e32 v132, 10, v0
	v_lshl_add_u64 v[0:1], v[132:133], 2, v[4:5]
	global_load_dwordx4 v[100:103], v[0:1], off
	v_add_lshl_u32 v132, s9, v205, 10
	v_lshl_add_u64 v[4:5], v[132:133], 2, v[4:5]
	global_load_dwordx4 v[104:107], v[4:5], off
	s_waitcnt vmcnt(0)
.Lpa_have_out1:
	v_add_u32_e32 v10, v203, v204
	v_add_u32_e32 v11, 0x400, v206
	v_add_u32_e32 v12, 0x400, v207
	v_add_u32_e32 v13, 0x2080, v10
	v_add_u32_e32 v14, 0x2088, v10
	v_add_u32_e32 v8, s6, v194
	v_ashrrev_i32_e32 v9, 31, v8
	v_readlane_b32 s36, v254, 41
	v_lshlrev_b64 v[8:9], 11, v[8:9]
	v_readlane_b32 s48, v254, 53
	v_readlane_b32 s49, v254, 54
	s_lshl_b32 s4, s8, 7
	v_readlane_b32 s37, v254, 42
	v_readlane_b32 s38, v254, 43
	v_readlane_b32 s39, v254, 44
	v_readlane_b32 s40, v254, 45
	v_readlane_b32 s41, v254, 46
	v_readlane_b32 s42, v254, 47
	v_readlane_b32 s43, v254, 48
	v_readlane_b32 s44, v254, 49
	v_readlane_b32 s45, v254, 50
	v_readlane_b32 s46, v254, 51
	v_readlane_b32 s47, v254, 52
	v_readlane_b32 s50, v254, 55
	v_readlane_b32 s51, v254, 56
	v_lshl_add_u64 v[8:9], s[48:49], 0, v[8:9]
	v_readlane_b32 s36, v254, 57
	v_lshlrev_b32_e32 v132, 1, v136
	v_lshl_add_u64 v[8:9], v[8:9], 0, s[4:5]
	v_readlane_b32 s37, v254, 58
	v_readlane_b32 s38, v254, 59
	v_readlane_b32 s39, v254, 60
	v_readlane_b32 s40, v254, 61
	v_readlane_b32 s41, v254, 62
	v_readlane_b32 s44, v255, 1
	v_readlane_b32 s45, v255, 2
	v_readlane_b32 s46, v255, 3
	v_readlane_b32 s47, v255, 4
	v_lshl_add_u64 v[8:9], v[8:9], 0, v[132:133]
	v_readlane_b32 s42, v254, 63
	v_readlane_b32 s43, v255, 0
	v_readlane_b32 s48, v255, 5
	v_readlane_b32 s49, v255, 6
	v_readlane_b32 s50, v255, 7
	v_readlane_b32 s51, v255, 8
	ds_write2_b32 v10, v100, v101 offset1:1
	ds_write2_b32 v10, v102, v103 offset0:2 offset1:3
	ds_write2_b32 v13, v104, v105 offset1:1
	ds_write2_b32 v14, v106, v107 offset1:1
	s_waitcnt lgkmcnt(0)
	s_barrier
	ds_read2_b32 v[0:1], v206 offset1:130
	ds_read2_b32 v[2:3], v207 offset0:65 offset1:195
	ds_read2_b32 v[4:5], v11 offset0:4 offset1:134
	ds_read2_b32 v[6:7], v12 offset0:69 offset1:199
	s_waitcnt lgkmcnt(2)
	v_cvt_pk_bf16_f32 v0, v0, v2
	v_cvt_pk_bf16_f32 v1, v1, v3
	s_waitcnt lgkmcnt(0)
	v_cvt_pk_bf16_f32 v2, v4, v6
	v_cvt_pk_bf16_f32 v3, v5, v7
	global_store_dwordx4 v[8:9], v[0:3], off
	s_barrier

.LBB0_38:
	s_andn2_b64 vcc, exec, s[6:7]
	s_cbranch_vccnz .LBB0_40
	s_add_i32 s4, s18, 0xfffffa40
	s_lshr_b32 s8, s4, 5
	s_lshl_b32 s6, s8, 11
	s_lshl_b32 s4, s4, 6
	s_lshl_b32 s9, s8, 6
	s_sub_i32 s6, s4, s6
	s_ashr_i32 s7, s6, 31
	s_cmp_lg_u32 s22, 0
	s_cbranch_scc1 .Lpa_have_in1
	v_or_b32_e32 v0, s9, v193
	v_lshl_add_u64 v[4:5], s[6:7], 2, v[140:141]
	v_lshlrev_b32_e32 v132, 11, v0
	v_lshl_add_u64 v[0:1], v[132:133], 2, v[4:5]
	global_load_dwordx4 v[100:103], v[0:1], off
	v_add_lshl_u32 v132, s9, v205, 11
	v_lshl_add_u64 v[4:5], v[132:133], 2, v[4:5]
	global_load_dwordx4 v[104:107], v[4:5], off
	s_waitcnt vmcnt(0)
.Lpa_have_in1:
	v_add_u32_e32 v10, v203, v204
	v_add_u32_e32 v11, 0x400, v206
	v_add_u32_e32 v12, 0x400, v207
	v_add_u32_e32 v13, 0x2080, v10
	v_add_u32_e32 v14, 0x2088, v10
	v_add_u32_e32 v8, s6, v194
	v_ashrrev_i32_e32 v9, 31, v8
	v_readlane_b32 s36, v254, 41
	v_lshlrev_b64 v[8:9], 11, v[8:9]
	v_readlane_b32 s46, v254, 51
	v_readlane_b32 s47, v254, 52
	s_lshl_b32 s4, s8, 7
	v_readlane_b32 s37, v254, 42
	v_readlane_b32 s38, v254, 43
	v_readlane_b32 s39, v254, 44
	v_readlane_b32 s40, v254, 45
	v_readlane_b32 s41, v254, 46
	v_readlane_b32 s42, v254, 47
	v_readlane_b32 s43, v254, 48
	v_readlane_b32 s44, v254, 49
	v_readlane_b32 s45, v254, 50
	v_readlane_b32 s48, v254, 53
	v_readlane_b32 s49, v254, 54
	v_readlane_b32 s50, v254, 55
	v_readlane_b32 s51, v254, 56
	v_lshl_add_u64 v[8:9], s[46:47], 0, v[8:9]
	v_readlane_b32 s36, v254, 57
	v_lshlrev_b32_e32 v132, 1, v136
	v_lshl_add_u64 v[8:9], v[8:9], 0, s[4:5]
	v_readlane_b32 s37, v254, 58
	v_readlane_b32 s38, v254, 59
	v_readlane_b32 s39, v254, 60
	v_readlane_b32 s40, v254, 61
	v_readlane_b32 s41, v254, 62
	v_readlane_b32 s44, v255, 1
	v_readlane_b32 s45, v255, 2
	v_readlane_b32 s46, v255, 3
	v_readlane_b32 s47, v255, 4
	v_lshl_add_u64 v[8:9], v[8:9], 0, v[132:133]
	v_readlane_b32 s42, v254, 63
	v_readlane_b32 s43, v255, 0
	v_readlane_b32 s48, v255, 5
	v_readlane_b32 s49, v255, 6
	v_readlane_b32 s50, v255, 7
	v_readlane_b32 s51, v255, 8
	ds_write2_b32 v10, v100, v101 offset1:1
	ds_write2_b32 v10, v102, v103 offset0:2 offset1:3
	ds_write2_b32 v13, v104, v105 offset1:1
	ds_write2_b32 v14, v106, v107 offset1:1
	s_waitcnt lgkmcnt(0)
	s_barrier
	ds_read2_b32 v[0:1], v206 offset1:130
	ds_read2_b32 v[2:3], v207 offset0:65 offset1:195
	ds_read2_b32 v[4:5], v11 offset0:4 offset1:134
	ds_read2_b32 v[6:7], v12 offset0:69 offset1:199
	s_waitcnt lgkmcnt(2)
	v_cvt_pk_bf16_f32 v0, v0, v2
	v_cvt_pk_bf16_f32 v1, v1, v3
	s_waitcnt lgkmcnt(0)
	v_cvt_pk_bf16_f32 v2, v4, v6
	v_cvt_pk_bf16_f32 v3, v5, v7
	global_store_dwordx4 v[8:9], v[0:3], off
	s_barrier

.LBB0_41:
	s_andn2_b64 vcc, exec, s[6:7]
	s_cbranch_vccnz .LBB0_43
	s_add_i32 s4, s18, 0xfffffb40
	s_lshr_b32 s8, s4, 4
	s_lshl_b32 s6, s8, 10
	s_lshl_b32 s4, s4, 6
	s_lshl_b32 s9, s8, 6
	s_sub_i32 s6, s4, s6
	s_ashr_i32 s7, s6, 31
	s_cmp_lg_u32 s22, 0
	s_cbranch_scc1 .Lpa_have_out0
	v_or_b32_e32 v0, s9, v193
	v_lshl_add_u64 v[4:5], s[6:7], 2, v[142:143]
	v_lshlrev_b32_e32 v132, 10, v0
	v_lshl_add_u64 v[0:1], v[132:133], 2, v[4:5]
	global_load_dwordx4 v[100:103], v[0:1], off
	v_add_lshl_u32 v132, s9, v205, 10
	v_lshl_add_u64 v[4:5], v[132:133], 2, v[4:5]
	global_load_dwordx4 v[104:107], v[4:5], off
	s_waitcnt vmcnt(0)
.Lpa_have_out0:
	v_add_u32_e32 v10, v203, v204
	v_add_u32_e32 v11, 0x400, v206
	v_add_u32_e32 v12, 0x400, v207
	v_add_u32_e32 v13, 0x2080, v10
	v_add_u32_e32 v14, 0x2088, v10
	v_add_u32_e32 v8, s6, v194
	v_ashrrev_i32_e32 v9, 31, v8
	v_readlane_b32 s36, v254, 41
	v_lshlrev_b64 v[8:9], 11, v[8:9]
	v_readlane_b32 s44, v254, 49
	v_readlane_b32 s45, v254, 50
	s_lshl_b32 s4, s8, 7
	v_readlane_b32 s37, v254, 42
	v_readlane_b32 s38, v254, 43
	v_readlane_b32 s39, v254, 44
	v_readlane_b32 s40, v254, 45
	v_readlane_b32 s41, v254, 46
	v_readlane_b32 s42, v254, 47
	v_readlane_b32 s43, v254, 48
	v_readlane_b32 s46, v254, 51
	v_readlane_b32 s47, v254, 52
	v_readlane_b32 s48, v254, 53
	v_readlane_b32 s49, v254, 54
	v_readlane_b32 s50, v254, 55
	v_readlane_b32 s51, v254, 56
	v_lshl_add_u64 v[8:9], s[44:45], 0, v[8:9]
	v_readlane_b32 s36, v254, 57
	v_lshlrev_b32_e32 v132, 1, v136
	v_lshl_add_u64 v[8:9], v[8:9], 0, s[4:5]
	v_readlane_b32 s37, v254, 58
	v_readlane_b32 s38, v254, 59
	v_readlane_b32 s39, v254, 60
	v_readlane_b32 s40, v254, 61
	v_readlane_b32 s41, v254, 62
	v_readlane_b32 s44, v255, 1
	v_readlane_b32 s45, v255, 2
	v_readlane_b32 s46, v255, 3
	v_readlane_b32 s47, v255, 4
	v_lshl_add_u64 v[8:9], v[8:9], 0, v[132:133]
	v_readlane_b32 s42, v254, 63
	v_readlane_b32 s43, v255, 0
	v_readlane_b32 s48, v255, 5
	v_readlane_b32 s49, v255, 6
	v_readlane_b32 s50, v255, 7
	v_readlane_b32 s51, v255, 8
	ds_write2_b32 v10, v100, v101 offset1:1
	ds_write2_b32 v10, v102, v103 offset0:2 offset1:3
	ds_write2_b32 v13, v104, v105 offset1:1
	ds_write2_b32 v14, v106, v107 offset1:1
	s_waitcnt lgkmcnt(0)
	s_barrier
	ds_read2_b32 v[0:1], v206 offset1:130
	ds_read2_b32 v[2:3], v207 offset0:65 offset1:195
	ds_read2_b32 v[4:5], v11 offset0:4 offset1:134
	ds_read2_b32 v[6:7], v12 offset0:69 offset1:199
	s_waitcnt lgkmcnt(2)
	v_cvt_pk_bf16_f32 v0, v0, v2
	v_cvt_pk_bf16_f32 v1, v1, v3
	s_waitcnt lgkmcnt(0)
	v_cvt_pk_bf16_f32 v2, v4, v6
	v_cvt_pk_bf16_f32 v3, v5, v7
	global_store_dwordx4 v[8:9], v[0:3], off
	s_barrier

.LBB0_44:
	s_andn2_b64 vcc, exec, s[6:7]
	s_cbranch_vccnz .LBB0_46
	s_add_i32 s4, s18, 0xffffff40
	s_and_b32 s6, s4, 0xffffffc0
	s_lshl_b32 s4, s4, 6
	s_and_b32 s8, s4, 0xfc0
	s_lshl_b32 s4, s8, 2
	s_cmp_lg_u32 s22, 0
	s_cbranch_scc1 .Lpa_have_in0
	v_or_b32_e32 v0, s6, v193
	v_lshl_add_u64 v[4:5], v[144:145], 0, s[4:5]
	v_lshlrev_b32_e32 v132, 12, v0
	v_lshl_add_u64 v[0:1], v[132:133], 2, v[4:5]
	global_load_dwordx4 v[100:103], v[0:1], off
	v_add_lshl_u32 v132, s6, v205, 12
	v_lshl_add_u64 v[4:5], v[132:133], 2, v[4:5]
	global_load_dwordx4 v[104:107], v[4:5], off
	s_waitcnt vmcnt(0)
.Lpa_have_in0:
	v_add_u32_e32 v10, v203, v204
	v_add_u32_e32 v11, 0x400, v206
	v_add_u32_e32 v12, 0x400, v207
	v_add_u32_e32 v13, 0x2080, v10
	v_add_u32_e32 v14, 0x2088, v10
	v_readlane_b32 s36, v254, 41
	v_add_lshl_u32 v132, s8, v194, 11
	v_readlane_b32 s42, v254, 47
	v_readlane_b32 s43, v254, 48
	s_mov_b32 s7, s5
	v_readlane_b32 s37, v254, 42
	v_readlane_b32 s38, v254, 43
	v_readlane_b32 s39, v254, 44
	v_readlane_b32 s40, v254, 45
	v_readlane_b32 s41, v254, 46
	v_readlane_b32 s44, v254, 49
	v_readlane_b32 s45, v254, 50
	v_readlane_b32 s46, v254, 51
	v_readlane_b32 s47, v254, 52
	v_readlane_b32 s48, v254, 53
	v_readlane_b32 s49, v254, 54
	v_readlane_b32 s50, v254, 55
	v_readlane_b32 s51, v254, 56
	v_lshl_add_u64 v[8:9], s[42:43], 0, v[132:133]
	v_readlane_b32 s36, v254, 57
	v_lshlrev_b32_e32 v132, 1, v136
	v_lshl_add_u64 v[8:9], s[6:7], 1, v[8:9]
	v_readlane_b32 s37, v254, 58
	v_readlane_b32 s38, v254, 59
	v_readlane_b32 s39, v254, 60
	v_readlane_b32 s40, v254, 61
	v_readlane_b32 s41, v254, 62
	v_readlane_b32 s44, v255, 1
	v_readlane_b32 s45, v255, 2
	v_readlane_b32 s46, v255, 3
	v_readlane_b32 s47, v255, 4
	v_lshl_add_u64 v[8:9], v[8:9], 0, v[132:133]
	v_readlane_b32 s42, v254, 63
	v_readlane_b32 s43, v255, 0
	v_readlane_b32 s48, v255, 5
	v_readlane_b32 s49, v255, 6
	v_readlane_b32 s50, v255, 7
	v_readlane_b32 s51, v255, 8
	ds_write2_b32 v10, v100, v101 offset1:1
	ds_write2_b32 v10, v102, v103 offset0:2 offset1:3
	ds_write2_b32 v13, v104, v105 offset1:1
	ds_write2_b32 v14, v106, v107 offset1:1
	s_waitcnt lgkmcnt(0)
	s_barrier
	ds_read2_b32 v[0:1], v206 offset1:130
	ds_read2_b32 v[2:3], v207 offset0:65 offset1:195
	ds_read2_b32 v[4:5], v11 offset0:4 offset1:134
	ds_read2_b32 v[6:7], v12 offset0:69 offset1:199
	s_waitcnt lgkmcnt(2)
	v_cvt_pk_bf16_f32 v0, v0, v2
	v_cvt_pk_bf16_f32 v1, v1, v3
	s_waitcnt lgkmcnt(0)
	v_cvt_pk_bf16_f32 v2, v4, v6
	v_cvt_pk_bf16_f32 v3, v5, v7
	global_store_dwordx4 v[8:9], v[0:3], off
	s_barrier
